# per-XCD dynamic differential units: ticket claimed at the key-loop exit (hidden by the combine epilogue) instead of at the unit start, so hand-out follows unit ends
# baseline (speedup 1.0000x reference)
.LBB0_552:
	s_cmpk_lg_u32 s24, 0x100
	s_cbranch_scc1 .Ldq_static
	v_readfirstlane_b32 s96, v225
	v_mov_b32_e32 v236, 0x20400
	s_nop 3
	s_cmp_ge_u32 s96, 64
	s_cbranch_scc1 .Ldq_nw
	s_waitcnt vmcnt(8)
	v_readfirstlane_b32 s98, v250
	v_mov_b32_e32 v237, s98
	ds_write_b32 v236, v237
	s_waitcnt lgkmcnt(0)

.LBB0_553:
	s_or_b32 s4, s63, s60
	v_mov_b32_e32 v233, v225
	s_bitcmp0_b32 s63, 0
	s_cselect_b32 s70, s59, s61
	v_readfirstlane_b32 s68, v233
	s_bfe_u32 s65, s68, 0x20006
	s_lshl_b32 s71, s70, 7
	s_lshl_b32 s67, s65, 5
	v_and_b32_e32 v231, 31, v233
	s_or_b32 s69, s67, s71
	s_add_i32 s40, s4, s62
	v_or_b32_e32 v212, s69, v231
	s_ashr_i32 s41, s40, 31
	s_ashr_i32 s66, s68, 8
	s_lshl_b64 s[42:43], s[40:41], 19
	v_lshl_add_u64 v[0:1], s[38:39], 0, v[212:213]
	s_add_u32 s72, s14, s42
	v_mad_u64_u32 v[2:3], s[40:41], v0, s44, v[214:215]
	s_addc_u32 s73, s15, s43
	v_mad_i32_i24 v3, v1, s44, v3
	s_lshl_b32 s64, s4, 7
	s_lshl_b32 s4, s4, 8
	s_lshl_b32 s40, s66, 6
	v_bfe_u32 v4, v233, 5, 1
	v_lshl_add_u64 v[0:1], v[2:3], 0, s[4:5]
	s_ashr_i32 s41, s40, 31
	v_lshl_add_u64 v[0:1], s[40:41], 1, v[0:1]
	v_lshlrev_b32_e32 v216, 4, v4
	v_mov_b32_e32 v217, v213
	v_lshl_add_u64 v[0:1], v[0:1], 0, v[216:217]
	v_lshl_add_u64 v[2:3], v[0:1], 0, s[6:7]
	v_add_co_u32_e32 v0, vcc, s45, v0
	s_add_u32 s42, s81, s42
	s_nop 0
	v_addc_co_u32_e32 v1, vcc, 0, v1, vcc
	global_load_dwordx4 v[128:131], v[2:3], off offset:32
	global_load_dwordx4 v[132:135], v[2:3], off offset:64
	global_load_dwordx4 v[136:139], v[0:1], off offset:2048
	global_load_dwordx4 v[140:143], v[2:3], off offset:96
	v_lshlrev_b32_e32 v0, 3, v233
	s_addc_u32 s43, s82, s43
	v_ashrrev_i32_e32 v1, 31, v0
	s_lshl_b32 s41, s70, 1
	v_lshlrev_b64 v[0:1], 1, v[0:1]
	v_mov_b32_e32 v246, v0
	v_add_u32_e32 v245, 0x2000, v0
	s_or_b32 s70, s41, 1
	s_mov_b64 s[88:89], s[72:73]
	v_lshl_add_u64 v[218:219], s[72:73], 0, v[0:1]
	s_lshl_b32 s4, s70, 14
	s_mov_b64 s[90:91], s[42:43]
	v_lshl_add_u64 v[220:221], s[42:43], 0, v[0:1]
	v_lshl_add_u64 v[0:1], v[218:219], 0, s[4:5]
	s_barrier
	v_lshl_add_u64 v[2:3], v[220:221], 0, s[4:5]
	global_load_dwordx4 v[144:147], v[0:1], off
	global_load_dwordx4 v[148:151], v[2:3], off
	v_add_co_u32_e32 v0, vcc, s47, v0
	v_lshlrev_b32_e32 v217, 3, v4
	s_nop 0
	v_addc_co_u32_e32 v1, vcc, 0, v1, vcc
	v_add_co_u32_e32 v2, vcc, s47, v2
	v_mul_u32_u24_e32 v230, 0x110, v231
	s_nop 0
	v_addc_co_u32_e32 v3, vcc, 0, v3, vcc
	global_load_dwordx4 v[152:155], v[0:1], off
	global_load_dwordx4 v[156:159], v[2:3], off
	v_lshrrev_b32_e32 v0, 4, v233
	v_lshlrev_b32_e32 v2, 4, v233
	v_mov_b32_e32 v1, 0x14e60
	v_lshrrev_b32_e32 v3, 3, v233
	v_mul_lo_u32 v5, v0, s46
	v_and_b32_e32 v0, 0x70, v2
	v_and_b32_e32 v6, 0xf0, v2
	v_mad_u64_u32 v[222:223], s[42:43], v3, s48, v[0:1]
	v_add3_u32 v234, 0, v5, v6
	v_add_u32_e32 v0, 0, v222
	v_or_b32_e32 v2, s40, v217
	v_lshlrev_b32_e32 v2, 1, v2
	v_mov_b32_e32 v48, v213
	v_mov_b32_e32 v49, v213
	v_mov_b32_e32 v62, v213
	v_mov_b32_e32 v63, v213
	v_lshlrev_b32_e32 v232, 2, v4
	v_add3_u32 v235, 0, v230, v2
	v_mad_u32_u24 v236, v231, s48, v1
	v_mov_b32_e32 v50, v213
	v_mov_b32_e32 v51, v213
	v_mov_b32_e32 v52, v213
	v_mov_b32_e32 v53, v213
	v_mov_b32_e32 v54, v213
	v_mov_b32_e32 v55, v213
	v_mov_b32_e32 v56, v213
	v_mov_b32_e32 v57, v213
	v_mov_b32_e32 v58, v213
	v_mov_b32_e32 v59, v213
	v_mov_b32_e32 v60, v213
	v_mov_b32_e32 v61, v213
	v_mov_b64_e32 v[32:33], v[48:49]
	v_mov_b64_e32 v[16:17], v[48:49]
	s_waitcnt vmcnt(8)
	v_mov_b64_e32 v[78:79], v[62:63]
	s_mov_b32 s72, 1
	s_waitcnt vmcnt(3)
	ds_write_b128 v234, v[144:147]
	s_waitcnt vmcnt(2)
	ds_write_b128 v0, v[148:151] offset:34816
	s_waitcnt vmcnt(1)
	ds_write_b128 v234, v[152:155] offset:8704
	s_waitcnt vmcnt(0)
	ds_write_b128 v0, v[156:159] offset:44032
	v_mov_b32_e32 v0, 0x14e40
	v_mad_u32_u24 v237, v231, s48, v0
	v_mov_b32_e32 v0, 0x14e20
	v_mad_u32_u24 v238, v231, s48, v0
	v_mov_b32_e32 v0, 0x14e00
	v_mad_u32_u24 v239, v231, s48, v0
	v_mov_b32_e32 v0, 0x13c00
	v_mad_u32_u24 v240, v231, s48, v0
	v_mov_b32_e32 v0, 0x12a60
	v_mad_u32_u24 v241, v231, s48, v0
	v_mov_b32_e32 v0, 0x12a40
	v_mad_u32_u24 v242, v231, s48, v0
	v_mov_b32_e32 v0, 0x12a20
	v_mad_u32_u24 v243, v231, s48, v0
	v_mov_b32_e32 v0, 0x12a00
	v_mad_u32_u24 v244, v231, s48, v0
	v_mov_b32_e32 v0, 0x11800
	v_mad_u32_u24 v248, v231, s48, v0
	v_add_u32_e32 v248, v248, v216
	v_mov_b64_e32 v[0:1], v[48:49]
	s_mov_b32 s73, 0
	s_mov_b32 s74, 2
	s_or_b32 s75, s69, 31
	s_mov_b64 s[42:43], 0
	v_mov_b32_e32 v224, 1.0
	v_mov_b32_e32 v249, 0xf149f2ca
	v_mov_b32_e32 v223, 0
	s_mov_b32 s4, s41
	v_mov_b64_e32 v[34:35], v[50:51]
	v_mov_b64_e32 v[36:37], v[52:53]
	v_mov_b64_e32 v[38:39], v[54:55]
	v_mov_b64_e32 v[40:41], v[56:57]
	v_mov_b64_e32 v[42:43], v[58:59]
	v_mov_b64_e32 v[44:45], v[60:61]
	v_mov_b64_e32 v[46:47], v[62:63]
	v_mov_b64_e32 v[18:19], v[50:51]
	v_mov_b64_e32 v[20:21], v[52:53]
	v_mov_b64_e32 v[22:23], v[54:55]
	v_mov_b64_e32 v[24:25], v[56:57]
	v_mov_b64_e32 v[26:27], v[58:59]
	v_mov_b64_e32 v[28:29], v[60:61]
	v_mov_b64_e32 v[30:31], v[62:63]
	v_mov_b64_e32 v[2:3], v[50:51]
	v_mov_b64_e32 v[4:5], v[52:53]
	v_mov_b64_e32 v[6:7], v[54:55]
	v_mov_b64_e32 v[8:9], v[56:57]
	v_mov_b64_e32 v[10:11], v[58:59]
	v_mov_b64_e32 v[12:13], v[60:61]
	v_mov_b64_e32 v[14:15], v[62:63]
	v_mov_b64_e32 v[76:77], v[60:61]
	v_mov_b64_e32 v[74:75], v[58:59]
	v_mov_b64_e32 v[72:73], v[56:57]
	v_mov_b64_e32 v[70:71], v[54:55]
	v_mov_b64_e32 v[68:69], v[52:53]
	v_mov_b64_e32 v[66:67], v[50:51]
	v_mov_b64_e32 v[64:65], v[48:49]
	s_waitcnt lgkmcnt(0)
	s_barrier
	s_branch .LBB0_555
	s_nop 0
	s_nop 0
	s_nop 0
	s_nop 0
	s_nop 0
	s_nop 0
	s_nop 0
	s_nop 0
	s_nop 0

.LBB0_576:
	s_cmpk_lg_u32 s24, 0x100
	s_cbranch_scc1 .Ldq_noat
	s_cmp_ge_u32 s68, 64
	s_cbranch_scc1 .Ldq_noat
	s_lshl_b32 s94, s99, 6
	s_add_u32 s94, s94, 0x83600
	s_add_u32 s94, s22, s94
	s_addc_u32 s95, s23, 0
	s_mov_b64 s[92:93], exec
	s_mov_b64 exec, 1
	v_mov_b32_e32 v237, 0
	v_mov_b32_e32 v238, 1
	global_atomic_add v250, v237, v238, s[94:95] sc0
	s_mov_b64 exec, s[92:93]
